# sample-scan item: lines read later through dependent chains are touched once at item start (L2 prefetch)
# speedup vs baseline: 1.0126x; 1.0126x over previous
; #define LAS __attribute__((address_space(3)))
; __device__ __forceinline__ void sscan_item(const Args& A, LAS unsigned char* lds, int tid, int lane, int wave, int bg, int h) {
;     const bf16_t* Z = (const bf16_t*)(A.ws + WS_Z); bf16_t* MIX = (bf16_t*)(A.ws + WS_XN);
;     LAS float* ZS = (LAS float*)(lds + SC_ZS); LAS float* OP = (LAS float*)(lds + SC_OP); LAS float* YB = (LAS float*)(lds + SC_Y); LAS float* CB = (LAS float*)(lds + SC_C);
;     const int fr = lane & 15, q4 = lane >> 4;
;     const int mt = wave & 1, nt = wave >> 1, cl = nt * 16 + fr, cg_ = h * 64 + cl;
;     bf16x8 bw[2], ba[2];
; #pragma unroll
;     for (int ks = 0; ks < 2; ++ks) { bw[ks] = *(const bf16x8*)((const bf16_t*)(A.ws + WS_W2T) + cg_ * 64 + ks * 32 + q4 * 8); ba[ks] = *(const bf16x8*)((const bf16_t*)(A.ws + WS_A2T) + cg_ * 64 + ks * 32 + q4 * 8); }
;     const float w0c = A.w0[cg_], a0c = A.a0[cg_], kkc = A.k_k[cg_], kac = A.k_a[cg_];
;     const float rkl = A.r_k[h * 64 + lane], lnw = A.ln_w[h * 64 + lane], lnb = A.ln_b[h * 64 + lane];
;     const int vr = (tid >> 3) & 31, kq = tid & 7;
;     f32x4 s0pre[2][4];
; #pragma unroll
;     for (int rep = 0; rep < 2; ++rep) { const int b_ = bg * 4 + (tid >> 8) + 2 * rep; const float* S0_ = A.st_wkv + ((size_t)b_ * 8 + h) * 4096;
;         s0pre[rep][0] = *(const f32x4*)(S0_ + vr * 64 + kq * 8); s0pre[rep][1] = *(const f32x4*)(S0_ + vr * 64 + kq * 8 + 4);
;         s0pre[rep][2] = *(const f32x4*)(S0_ + (vr + 32) * 64 + kq * 8); s0pre[rep][3] = *(const f32x4*)(S0_ + (vr + 32) * 64 + kq * 8 + 4); }
; __global__ void __launch_bounds__(512, 2) hymba_fwd(Args A) {
;     ...
;             if (tid == 0) *s_item = (int)atomicAdd(ctl + CW_WORK + 2, 1u);
;             __syncthreads();
;             const int r = *s_item;
;             __syncthreads();
;             if (r >= 256) break;
;             sscan_item(A, lds, tid, lane, wave, r >> 3, r & 7);
.LBB0_324:
	s_or_b64 exec, exec, s[8:9]
	v_mov_b32_e32 v0, s18
	s_waitcnt lgkmcnt(0)
	s_barrier
	ds_read_b32 v0, v0
	s_movk_i32 s8, 0xff
	s_waitcnt lgkmcnt(0)
	s_barrier
	v_cmp_lt_i32_e32 vcc, s8, v0
	v_readfirstlane_b32 s10, v0
	s_mov_b64 s[8:9], -1
	s_cbranch_vccnz .LBB0_319
	s_lshr_b32 s98, s10, 3
	s_lshl_b32 s98, s98, 5
	s_add_i32 s98, s98, 0x8000
	s_mul_i32 s98, s98, 0x1c00
	s_add_u32 s98, s98, s94
	s_addc_u32 s99, s95, 0
	s_and_b32 s100, s10, 7
	s_lshl_b32 s100, s100, 7
	v_readlane_b32 s101, v249, 3
	v_mbcnt_lo_u32_b32 v250, -1, 0
	v_mbcnt_hi_u32_b32 v250, -1, v250
	v_and_b32_e32 v252, 31, v250
	v_mul_u32_u24_e32 v252, 0x1c00, v252
	s_cmp_lt_u32 s101, 3
	s_cbranch_scc0 .Lsspf_3
	s_lshl_b32 s101, s101, 10
	s_add_i32 s101, s101, s100
	v_add_u32_e32 v252, s101, v252
	s_mov_b64 exec, 0xffffffff
	global_load_dword v251, v252, s[98:99]
	s_mov_b64 exec, -1
	s_branch .Lsspf_done
.Lsspf_3:
	s_cmp_eq_u32 s101, 3
	s_cbranch_scc0 .Lsspf_4
	v_lshrrev_b32_e32 v253, 5, v250
	v_lshl_add_u32 v252, v253, 7, v252
	v_add_u32_e32 v252, 0xc00, v252
	global_load_dword v251, v252, s[98:99]
	s_branch .Lsspf_done
.Lsspf_4:
	s_cmp_eq_u32 s101, 4
	s_cbranch_scc0 .Lsspf_5
	s_add_i32 s101, s100, 0xd00
	v_add_u32_e32 v252, s101, v252
	s_mov_b64 exec, 0xffffffff
	global_load_dword v251, v252, s[98:99]
	s_mov_b64 exec, -1
	s_branch .Lsspf_done
.Lsspf_5:
	s_cmp_lt_u32 s101, 7
	s_cbranch_scc0 .Lsspf_done
	v_readlane_b32 s98, v249, 20
	v_readlane_b32 s99, v249, 21
	s_lshr_b32 vcc_lo, s10, 3
	s_mul_i32 vcc_lo, vcc_lo, 0x6800
	s_add_u32 s98, s98, vcc_lo
	s_addc_u32 s99, s99, 0
	s_cmp_eq_u32 s101, 5
	s_cbranch_scc0 .Lsspf_6
	v_lshrrev_b32_e32 v252, 3, v250
	v_mul_u32_u24_e32 v252, 0x1a00, v252
	v_and_b32_e32 v253, 7, v250
	v_lshrrev_b32_e32 v251, 1, v253
	v_lshl_add_u32 v252, v251, 11, v252
	v_and_b32_e32 v251, 1, v253
	v_lshl_add_u32 v252, v251, 7, v252
	s_lshl_b32 s100, s100, 1
	v_add_u32_e32 v252, s100, v252
	v_cmp_gt_u32_e32 vcc, 6, v253
	s_and_b64 vcc, vcc, 0xffffffff
	s_mov_b64 exec, vcc
	global_load_dword v251, v252, s[98:99]
	s_mov_b64 exec, -1
	s_branch .Lsspf_done
.Lsspf_6:
	v_lshrrev_b32_e32 v252, 2, v250
	v_mul_u32_u24_e32 v252, 0x1a00, v252
	v_and_b32_e32 v253, 3, v250
	v_lshl_add_u32 v252, v253, 7, v252
	v_add_u32_e32 v252, 0x1800, v252
	s_mov_b64 exec, 0xffff
	global_load_dword v251, v252, s[98:99]
	s_mov_b64 exec, -1
.Lsspf_done:
	s_and_b32 s65, s10, 7
	s_lshl_b32 s78, s65, 6
	v_add_u32_e32 v4, s78, v162
	v_lshlrev_b32_e32 v76, 7, v4
	v_lshl_add_u64 v[0:1], v[80:81], 0, v[76:77]
	v_lshl_add_u64 v[2:3], v[82:83], 0, v[76:77]
	global_load_dwordx4 v[40:43], v[0:1], off
	global_load_dwordx4 v[32:35], v[0:1], off offset:64
	global_load_dwordx4 v[44:47], v[2:3], off
	global_load_dwordx4 v[36:39], v[2:3], off offset:64
	v_lshlrev_b32_e32 v0, 2, v4
	global_load_dword v199, v0, s[62:63]
	global_load_dword v198, v0, s[66:67]
	global_load_dword v197, v0, s[70:71]
	global_load_dword v196, v0, s[72:73]
	v_or_b32_e32 v0, s78, v145
	v_readlane_b32 s24, v249, 10
	s_ashr_i32 s8, s10, 1
	v_lshlrev_b32_e32 v0, 2, v0
	v_readlane_b32 s25, v249, 11
	s_and_b32 s64, s8, -4
	global_load_dword v195, v0, s[74:75]
	v_readlane_b32 s26, v249, 12
	v_readlane_b32 s27, v249, 13
	s_nop 0
	global_load_dword v194, v0, s[24:25]
	s_nop 2
	global_load_dword v193, v0, s[26:27]
	v_or_b32_e32 v0, s64, v72
	s_lshl_b32 s10, s65, 14
	v_ashrrev_i32_e32 v1, 31, v0
	v_lshl_add_u64 v[2:3], v[86:87], 0, s[10:11]
	v_lshlrev_b64 v[92:93], 17, v[0:1]
	v_lshl_add_u64 v[0:1], v[2:3], 0, v[92:93]
	v_lshlrev_b32_e32 v90, 2, v88
	v_mov_b32_e32 v91, v77
	v_lshl_add_u64 v[4:5], v[0:1], 0, v[90:91]
	v_add_co_u32_e32 v2, vcc, s19, v4
	v_lshl_add_u64 v[0:1], v[4:5], 0, s[22:23]
	s_nop 0
	v_addc_co_u32_e32 v3, vcc, 0, v5, vcc
	s_mov_b64 s[8:9], 0x40000
	global_load_dwordx4 v[16:19], v[4:5], off offset:16
	global_load_dwordx4 v[24:27], v[4:5], off
	global_load_dwordx4 v[28:31], v[2:3], off
	global_load_dwordx4 v[20:23], v[0:1], off offset:16
	v_lshl_add_u64 v[0:1], v[4:5], 0, s[8:9]
	s_mov_b32 s8, 0x40000
	v_add_co_u32_e32 v2, vcc, s8, v4
	s_mov_b64 s[8:9], 0x42000
	s_nop 0
	v_addc_co_u32_e32 v3, vcc, 0, v5, vcc
	v_lshl_add_u64 v[6:7], v[4:5], 0, s[8:9]
	v_add_co_u32_e32 v4, vcc, 0x42000, v4
	global_load_dwordx4 v[8:11], v[2:3], off
	s_nop 0
	global_load_dwordx4 v[0:3], v[0:1], off offset:16
	v_addc_co_u32_e32 v5, vcc, 0, v5, vcc
	global_load_dwordx4 v[12:15], v[4:5], off
	s_nop 0
	global_load_dwordx4 v[4:7], v[6:7], off offset:16
	s_lshl_b32 s10, s65, 12
	s_or_b32 s79, s78, 0x400
	s_or_b32 s80, s78, 0x200
	s_mov_b64 s[24:25], 0
	v_mov_b32_e32 v91, v144
	s_branch .LBB0_328
